# speedup vs baseline: 1.0065x; 1.0027x over previous
.LBB0_601:
	s_or_b64 exec, exec, s[0:1]
	v_mov_b32_e32 v220, v218
	s_cmpk_lt_i32 s70, 0x200
	s_waitcnt lgkmcnt(0)
	s_barrier
	s_cselect_b64 s[10:11], -1, 0
	s_cmpk_gt_i32 s70, 0x1ff
	v_readfirstlane_b32 s12, v220
	s_cbranch_scc1 .LBB0_604
	s_bfe_u32 s99, s70, 0x10001
	s_lshl_b32 s99, s99, 8
	s_add_i32 s99, s99, s70
	s_ashr_i32 s0, s99, 31
	s_lshr_b32 s0, s0, 29
	s_add_i32 s2, s99, s0
	s_and_b32 s0, s2, -8
	s_sub_i32 s3, s99, s0
	s_cmp_gt_i32 s3, -1
	s_cbranch_scc0 .LBB0_605
	s_lshl_b32 s4, s3, 6
	s_cbranch_execz .LBB0_606
	s_branch .LBB0_607

.LBB0_613:
	s_add_i32 s50, s50, 1
	s_bfe_u32 s98, s70, 0x10001
	s_add_i32 s98, s98, s50
	s_and_b32 s98, s98, 1
	s_mul_i32 s10, s98, s62
	s_add_i32 s10, s10, s70
	s_cmpk_lt_i32 s50, 2
	s_cselect_b64 s[34:35], -1, 0
	s_cmpk_gt_i32 s50, 1
	s_cbranch_scc1 .LBB0_619
	s_ashr_i32 s5, s10, 31
	s_lshr_b32 s5, s5, 29
	s_add_i32 s5, s10, s5
	s_and_b32 s11, s5, -8
	s_sub_i32 s12, s10, s11
	s_cmp_gt_i32 s12, -1
	s_mov_b64 s[10:11], -1
	s_cbranch_scc0 .LBB0_616
	s_lshl_b32 s13, s12, 6
	s_mov_b64 s[10:11], 0

.LBB0_1064:
	s_or_b64 exec, exec, s[0:1]
	v_mov_b32_e32 v154, v218
	s_waitcnt lgkmcnt(0)
	s_barrier
	s_and_b64 vcc, exec, s[8:9]
	v_readfirstlane_b32 s7, v154
	s_cbranch_vccnz .LBB0_1088
	s_bfe_u32 s99, s70, 0x10001
	s_lshl_b32 s99, s99, 8
	s_add_i32 s99, s99, s70
	s_ashr_i32 s0, s99, 31
	s_lshr_b32 s0, s0, 29
	s_add_i32 s4, s99, s0
	s_and_b32 s0, s4, -8
	s_sub_i32 s2, s99, s0
	s_cmp_gt_i32 s2, -1
	s_cbranch_scc0 .LBB0_1067
	s_lshl_b32 s3, s2, 6
	s_ashr_i32 s0, s4, 3
	s_cbranch_execz .LBB0_1068
	s_branch .LBB0_1069

.LBB0_1074:
	s_add_i32 s37, s37, 1
	s_bfe_u32 s98, s70, 0x10001
	s_add_i32 s98, s98, s37
	s_and_b32 s98, s98, 1
	s_mul_i32 s21, s98, s62
	s_add_i32 s21, s21, s70
	s_cmpk_lt_i32 s37, 2
	s_cselect_b64 s[18:19], -1, 0
	s_cmpk_gt_i32 s37, 1
	s_cbranch_scc1 .LBB0_1080
	s_ashr_i32 s20, s21, 31
	s_lshr_b32 s20, s20, 29
	s_add_i32 s22, s21, s20
	s_and_b32 s20, s22, -8
	s_sub_i32 s23, s21, s20
	s_cmp_gt_i32 s23, -1
	s_mov_b64 s[20:21], -1
	s_cbranch_scc0 .LBB0_1077
	s_lshl_b32 s24, s23, 6
	s_mov_b64 s[20:21], 0
